# P0: waves 4-7 run the VALU-bound filter MLP first while waves 0-3 stream the transposes, then swap (overlap across segments)
# speedup vs baseline: 1.0096x; 1.0096x over previous
; #define LAS __attribute__((address_space(3)))
; __device__ __forceinline__ unsigned xb_add(unsigned* p, unsigned v) { return __hip_atomic_fetch_add(p, v, __ATOMIC_RELAXED, __HIP_MEMORY_SCOPE_AGENT); }
; __device__ __forceinline__ unsigned xb_xcc_id() { return (unsigned)__builtin_amdgcn_s_getreg((3 << 11) | 20) & 0xFu; }
; __device__ __forceinline__ XcdBarrier xcd_barrier_post(unsigned* bar, volatile LAS unsigned* st) {
;     XcdBarrier b; b.bar = bar; b.x = xb_xcc_id(); b.st = st;
;     if (threadIdx.x == 0) (void)xb_add(&bar[XB_XCNT(b.x)], 1u);
;     return b;
; }
; __global__ void __launch_bounds__(512) fwd_kernel(Args args) {
;     extern __shared__ __attribute__((aligned(16))) unsigned char lds_raw[];
;     Frame F; F.lds = (LAS unsigned char*)lds_raw; F.tid = threadIdx.x; F.lane = F.tid & 63; F.wave = __builtin_amdgcn_readfirstlane(F.tid >> 6); F.G = gridDim.x; F.bid = blockIdx.x;
;     cg::grid_group grid = cg::this_grid();
;     volatile LAS unsigned* BST = (volatile LAS unsigned*)(F.lds + LDS_BYTES - 64);
;     if (F.tid < 2) BST[F.tid] = 0u;
;     __syncthreads();
;     XcdBarrier xbar; xbar.bar = (unsigned*)(args.ws + WS_BAR); xbar.x = 0; xbar.st = BST;
;     ...
;     xbar = xcd_barrier_post((unsigned*)(args.ws + WS_BAR), BST);
_Z10fwd_kernel4Args:
	s_mov_b32 s99, 0
	s_load_dwordx8 s[68:75], s[0:1], 0xe0
	s_load_dwordx8 s[4:11], s[0:1], 0xc0
	s_load_dword s97, s[0:1], 0x100
	v_and_b32_e32 v221, 0x3ff, v0
	v_cmp_gt_u32_e32 vcc, 2, v221
	v_readfirstlane_b32 s33, v221
	s_waitcnt lgkmcnt(0)
	v_writelane_b32 v248, s4, 0
	s_nop 1
	v_writelane_b32 v248, s5, 1
	v_writelane_b32 v248, s6, 2
	v_writelane_b32 v248, s7, 3
	v_writelane_b32 v248, s8, 4
	v_writelane_b32 v248, s9, 5
	v_writelane_b32 v248, s10, 6
	v_writelane_b32 v248, s11, 7
	s_add_u32 s6, s0, 0xf8
	s_addc_u32 s7, s1, 0
	s_and_saveexec_b64 s[4:5], vcc
	v_lshl_add_u32 v1, v221, 2, 0
	v_add_u32_e32 v1, 0x23fc0, v1
	v_mov_b32_e32 v2, 0
	ds_write_b32 v1, v2
	s_or_b64 exec, exec, s[4:5]
	s_waitcnt lgkmcnt(0)
	s_barrier
	s_add_u32 s94, s70, 0x300000
	s_getreg_b32 s3, hwreg(HW_REG_XCC_ID, 0, 4)
	s_addc_u32 s95, s71, 0
	s_and_b32 s96, s3, 15
	v_cmp_eq_u32_e64 s[8:9], 0, v221
	s_mov_b64 s[4:5], exec
	s_nop 0
	v_writelane_b32 v248, s8, 8
	s_nop 1
	v_writelane_b32 v248, s9, 9
	s_and_b64 s[8:9], s[4:5], s[8:9]
	s_mov_b64 exec, s[8:9]
	s_cbranch_execz .LBB0_5
	s_mov_b64 s[8:9], exec
	v_mbcnt_lo_u32_b32 v1, s8, 0
	v_mbcnt_hi_u32_b32 v1, s9, v1
	v_cmp_eq_u32_e32 vcc, 0, v1
	s_and_b64 s[10:11], exec, vcc
	s_mov_b64 exec, s[10:11]
	s_cbranch_execz .LBB0_5
	s_lshl_b32 s3, s96, 8
	s_bcnt1_i32_b64 s8, s[8:9]
	v_mov_b32_e32 v1, s3
	v_mov_b32_e32 v2, s8
	global_atomic_add v1, v2, s[94:95] offset:1024

; #define LAS __attribute__((address_space(3)))
; #define REP(k) for (int rep_ = 0; rep_ < ((PROBE_DOUBLE) == (k) ? 2 : 1); ++rep_)
; __device__ __forceinline__ void transpose_matrix(const Frame& F, const float* W, int K, int N, const float* gain, bf16* WT, int kind, int& base) {
;     LAS float* scr = (LAS float*)(F.lds + F.wave * 17408);
;     const int nblk = N / 64, nitems = (K / 64) * nblk, gw = F.bid * 8 + F.wave, NGW = F.G * 8;
;     int first = (gw - (base % NGW) + NGW) % NGW;
;     for (int it = first; it < nitems; it += NGW) { const int kb = it / nblk, nb = it % nblk, n0 = nb * 64;
;         int r0 = n0; if (kind) r0 = 256 * (n0 / 128) + (n0 % 128) + (kind == 2 ? 128 : 0);
;         transpose_item(W, K, N, gain, WT, r0, scr, kb * 64, n0, F.lane); }
;     base += nitems;
; }
; __global__ void __launch_bounds__(512) fwd_kernel(Args args) {
;     ...
;     if (IN(0)) REP(0) {
;         int base = 0;
;         transpose_matrix(F, args.in[I_HWIN], 1024, 3072, args.in[I_NMIX], Whin, 0, base);
.LBB0_17:
	s_add_u32 s30, s70, 0x400000
	s_addc_u32 s31, s71, 0
	s_add_u32 s28, s70, 0xa00000
	s_addc_u32 s29, s71, 0
	s_add_u32 s4, s70, 0xc00000
	s_addc_u32 s5, s71, 0
	v_writelane_b32 v248, s4, 10
	s_load_dwordx16 s[12:27], s[0:1], 0x80
	v_and_b32_e32 v220, 63, v221
	v_writelane_b32 v248, s5, 11
	s_add_u32 s4, s70, 0x1200000
	s_addc_u32 s5, s71, 0
	s_lshr_b32 s89, s33, 6
	v_writelane_b32 v248, s4, 12
	s_cmp_lt_i32 s72, 1
	s_nop 0
	v_writelane_b32 v248, s5, 13
	s_cselect_b64 s[4:5], -1, 0
	s_cmp_gt_i32 s73, 0
	s_cselect_b64 s[6:7], -1, 0
	s_and_b64 s[34:35], s[4:5], s[6:7]
	s_andn2_b64 vcc, exec, s[34:35]
	v_writelane_b32 v248, s33, 14
	s_cbranch_vccnz .LBB0_170
	s_lshl_b32 s88, s74, 3
	s_abs_i32 s3, s88
	v_cvt_f32_u32_e32 v0, s3
	s_lshl_b32 s5, s2, 3
	s_add_i32 s90, s89, s5
	s_sub_i32 s5, 0, s3
	v_rcp_iflag_f32_e32 v0, v0
	s_add_i32 s33, s90, s88
	s_abs_i32 s7, s33
	s_mul_i32 s4, s89, 0x4400
	v_mul_f32_e32 v0, 0x4f7ffffe, v0
	v_cvt_u32_f32_e32 v0, v0
	s_add_i32 s4, s4, 0
	s_ashr_i32 s6, s33, 31
	v_lshrrev_b32_e32 v64, 4, v220
	v_readfirstlane_b32 s76, v0
	s_mul_i32 s5, s5, s76
	s_mul_hi_u32 s5, s76, s5
	s_add_i32 s76, s76, s5
	s_mul_hi_u32 s5, s7, s76
	s_mul_i32 s5, s5, s3
	s_sub_i32 s5, s7, s5
	s_sub_i32 s7, s5, s3
	s_cmp_ge_u32 s5, s3
	s_cselect_b32 s5, s7, s5
	s_sub_i32 s7, s5, s3
	s_cmp_ge_u32 s5, s3
	s_cselect_b32 s5, s7, s5
	s_xor_b32 s5, s5, s6
	s_sub_i32 s52, s5, s6
	s_movk_i32 s5, 0x104
	v_mov_b32_e32 v1, 0x410
	v_mad_u32_u24 v76, v64, s5, v1
	v_mov_b32_e32 v1, 0x820
	v_mad_u32_u24 v85, v64, s5, v1
	v_mov_b32_e32 v1, 0xc30
	v_mad_u32_u24 v86, v64, s5, v1
	v_mov_b32_e32 v1, 0x1040
	v_mad_u32_u24 v87, v64, s5, v1
	v_mov_b32_e32 v1, 0x1450
	v_mad_u32_u24 v88, v64, s5, v1
	v_mov_b32_e32 v1, 0x1860
	v_mad_u32_u24 v77, v64, s5, v1
	v_mov_b32_e32 v1, 0x1c70
	v_mad_u32_u24 v89, v64, s5, v1
	v_mov_b32_e32 v1, 0x2080
	v_mad_u32_u24 v90, v64, s5, v1
	v_mov_b32_e32 v1, 0x2490
	v_mad_u32_u24 v91, v64, s5, v1
	v_mov_b32_e32 v1, 0x28a0
	v_mad_u32_u24 v92, v64, s5, v1
	v_mov_b32_e32 v1, 0x2cb0
	v_lshlrev_b32_e32 v82, 2, v221
	v_mad_u32_u24 v78, v64, s5, v1
	v_lshlrev_b32_e32 v1, 3, v221
	v_and_b32_e32 v0, 60, v82
	v_lshrrev_b32_e32 v93, 3, v220
	v_and_b32_e32 v1, 56, v1
	v_lshl_add_u32 v83, v0, 2, s4
	v_mul_u32_u24_e32 v2, 0x104, v1
	v_lshlrev_b32_e32 v3, 2, v93
	s_cmp_lg_u32 s99, 0
	s_cbranch_scc1 .Lp0_go_A
	v_readlane_b32 s98, v248, 14
	s_nop 3
	s_cmp_lt_u32 s98, 0x100
	s_cbranch_scc1 .Lp0_go_A
	s_mov_b32 s99, 1
	s_waitcnt lgkmcnt(0)
	v_writelane_b32 v249, s0, 0
	v_writelane_b32 v249, s1, 1
	v_writelane_b32 v249, s36, 2
	v_writelane_b32 v249, s37, 3
	v_writelane_b32 v249, s38, 4
	v_writelane_b32 v249, s39, 5
	v_writelane_b32 v249, s40, 6
	v_writelane_b32 v249, s41, 7
	v_writelane_b32 v249, s42, 8
	v_writelane_b32 v249, s43, 9
	v_writelane_b32 v249, s44, 10
	v_writelane_b32 v249, s45, 11
	v_writelane_b32 v249, s46, 12
	v_writelane_b32 v249, s47, 13
	v_writelane_b32 v249, s48, 14
	v_writelane_b32 v249, s49, 15
	v_writelane_b32 v249, s50, 16
	v_writelane_b32 v249, s51, 17
	s_load_dwordx16 s[52:67], s[0:1], 0x40
	s_waitcnt lgkmcnt(0)
	s_branch .Lp0_mlp_entry
.Lp0_go_A:
	s_cmpk_gt_i32 s52, 0x2ff
	v_mov_b32_e32 v65, 0
	v_mad_u32_u24 v84, v64, s5, v83
	v_add3_u32 v94, s4, v2, v3
	v_lshlrev_b32_e32 v68, 2, v0
	v_lshlrev_b32_e32 v66, 1, v1
	s_cbranch_scc1 .LBB0_53
	s_waitcnt lgkmcnt(0)
	s_cmp_lg_u64 s[38:39], 0
	s_cselect_b64 s[4:5], -1, 0
	v_mov_b32_e32 v69, v65
	v_mov_b32_e32 v67, v65
	v_cndmask_b32_e64 v0, 0, 1, s[4:5]
	v_lshl_add_u64 v[70:71], s[44:45], 0, v[68:69]
	v_lshl_add_u64 v[72:73], s[30:31], 0, v[66:67]
	s_lshl_b32 s44, s52, 6
	s_lshl_b32 s45, s88, 6
	s_movk_i32 s53, 0x3000
	v_cmp_ne_u32_e64 s[4:5], 1, v0
	s_branch .LBB0_22

; __device__ __forceinline__ void filter_mlp(const Frame& F, const float* w1, const float* b1, const float* w2, const float* b2, const float* w3, const float* b3, const float* freq, bf16* HF) {
;     const int gw = F.bid * 8 + F.wave, NGW = F.G * 8, lane = F.lane;
;     const float fr = freq[lane], bb1 = b1[lane], bb2 = b2[lane], bb3 = b3[lane];
;     const float band = 1e-4f + (float)(lane & 15) * ((15.0f - 1e-4f) / 15.0f);
;     float W1r[33], W2r[64], W3r[64];
; #pragma unroll
;     for (int i = 0; i < 33; ++i) W1r[i] = w1[i * 64 + lane];
; #pragma unroll
;     for (int k = 0; k < 64; ++k) { W2r[k] = w2[k * 64 + lane]; W3r[k] = w3[k * 64 + lane]; }
;     for (int pos = gw; pos < SEQL; pos += NGW) {
.LBB0_145:
	s_cmp_eq_u32 s99, 2
	s_cbranch_scc1 .LBB0_169

; __device__ __forceinline__ void filter_mlp(const Frame& F, const float* w1, const float* b1, const float* w2, const float* b2, const float* w3, const float* b3, const float* freq, bf16* HF) {
;     const int gw = F.bid * 8 + F.wave, NGW = F.G * 8, lane = F.lane;
;     const float fr = freq[lane], bb1 = b1[lane], bb2 = b2[lane], bb3 = b3[lane];
;     const float band = 1e-4f + (float)(lane & 15) * ((15.0f - 1e-4f) / 15.0f);
;     float W1r[33], W2r[64], W3r[64];
; #pragma unroll
;     for (int i = 0; i < 33; ++i) W1r[i] = w1[i * 64 + lane];
; #pragma unroll
;     for (int k = 0; k < 64; ++k) { W2r[k] = w2[k * 64 + lane]; W3r[k] = w3[k * 64 + lane]; }
;     for (int pos = gw; pos < SEQL; pos += NGW) {
;         const float t = (float)pos * (1.0f / (float)(SEQL - 1));
;         const float w = 6.283185307179586f * (float)pos / (float)SEQL;
;         const float arg = band * w; const float c = cosf(arg), s = -sinf(arg);
;         float a = bb1 + t * W1r[0];
; #pragma unroll
;         for (int i = 0; i < 16; ++i) a += rdl(c, i) * W1r[1 + i] + rdl(s, i) * W1r[17 + i];
;         float h = sinf(fr * a);
;         a = bb2;
; #pragma unroll
;         for (int k = 0; k < 64; ++k) a += rdl(h, k) * W2r[k];
;         h = sinf(fr * a);
;         a = bb3;
; #pragma unroll
;         for (int k = 0; k < 64; ++k) a += rdl(h, k) * W3r[k];
;         h = sinf(fr * a);
;         HF[(size_t)pos * 128 + lane] = (bf16)f2bf(h); HF[(size_t)pos * 128 + 64 + lane] = 0;
;     }
; }
; __global__ void __launch_bounds__(512) fwd_kernel(Args args) {
;     ...
;     if (IN(0)) REP(0) {
;         int base = 0;
;         transpose_matrix(F, args.in[I_HWIN], 1024, 3072, args.in[I_NMIX], Whin, 0, base);
;         transpose_matrix(F, args.in[I_HWOUT], 1024, 1024, nullptr, Whout, 0, base);
;         transpose_matrix(F, args.in[I_NWQKV], 1024, 3072, args.in[I_NMIX] + 1024, Wqkv, 0, base);
;         transpose_matrix(F, args.in[I_NWO], 1024, 1024, nullptr, Wo, 0, base);
;         for (int l = 0; l < 2; ++l) {
;             bf16* gu = (bf16*)(ws + (l ? WS_WGU1 : WS_WGU0)); bf16* wd = (bf16*)(ws + (l ? WS_WD1 : WS_WD0));
;             transpose_matrix(F, args.in[I_WG] + (size_t)l * 1024 * FFH, 1024, FFH, args.in[I_NFFN] + l * 1024, gu, 1, base);
;             transpose_matrix(F, args.in[I_WU] + (size_t)l * 1024 * FFH, 1024, FFH, args.in[I_NFFN] + l * 1024, gu, 2, base);
.LBB0_169:
	s_cmp_eq_u32 s99, 1
	s_cbranch_scc0 .Lp0_end
	s_mov_b32 s99, 2
	v_readlane_b32 s0, v249, 0
	v_readlane_b32 s1, v249, 1
	v_readlane_b32 s36, v249, 2
	v_readlane_b32 s37, v249, 3
	v_readlane_b32 s38, v249, 4
	v_readlane_b32 s39, v249, 5
	v_readlane_b32 s40, v249, 6
	v_readlane_b32 s41, v249, 7
	v_readlane_b32 s42, v249, 8
	v_readlane_b32 s43, v249, 9
	v_readlane_b32 s44, v249, 10
	v_readlane_b32 s45, v249, 11
	v_readlane_b32 s46, v249, 12
	v_readlane_b32 s47, v249, 13
	v_readlane_b32 s48, v249, 14
	v_readlane_b32 s49, v249, 15
	v_readlane_b32 s50, v249, 16
	v_readlane_b32 s51, v249, 17
	v_readlane_b32 s33, v248, 14
	s_mov_b64 exec, -1
	s_nop 4
	s_branch .LBB0_17

; #define LAS __attribute__((address_space(3)))
; __global__ void __launch_bounds__(512) fwd_kernel(Args args) {
;     extern __shared__ __attribute__((aligned(16))) unsigned char lds_raw[];
;     Frame F; F.lds = (LAS unsigned char*)lds_raw; F.tid = threadIdx.x; F.lane = F.tid & 63; F.wave = __builtin_amdgcn_readfirstlane(F.tid >> 6); F.G = gridDim.x; F.bid = blockIdx.x;
	.amdhsa_kernel _Z10fwd_kernel4Args
		.amdhsa_group_segment_fixed_size 0
		.amdhsa_private_segment_fixed_size 0
		.amdhsa_kernarg_size 504
		.amdhsa_user_sgpr_count 2
		.amdhsa_user_sgpr_dispatch_ptr 0
		.amdhsa_user_sgpr_queue_ptr 0
		.amdhsa_user_sgpr_kernarg_segment_ptr 1
		.amdhsa_user_sgpr_dispatch_id 0
		.amdhsa_user_sgpr_kernarg_preload_length 0
		.amdhsa_user_sgpr_kernarg_preload_offset 0
		.amdhsa_user_sgpr_private_segment_size 0
		.amdhsa_uses_dynamic_stack 0
		.amdhsa_enable_private_segment 0
		.amdhsa_system_sgpr_workgroup_id_x 1
		.amdhsa_system_sgpr_workgroup_id_y 0
		.amdhsa_system_sgpr_workgroup_id_z 0
		.amdhsa_system_sgpr_workgroup_info 0
		.amdhsa_system_vgpr_workitem_id 2
		.amdhsa_next_free_vgpr 250
		.amdhsa_next_free_sgpr 100
		.amdhsa_accum_offset 252
		.amdhsa_reserve_vcc 1
		.amdhsa_float_round_mode_32 0
		.amdhsa_float_round_mode_16_64 0
		.amdhsa_float_denorm_mode_32 3
		.amdhsa_float_denorm_mode_16_64 3
		.amdhsa_dx10_clamp 1
		.amdhsa_ieee_mode 1
		.amdhsa_fp16_overflow 0
		.amdhsa_tg_split 0
		.amdhsa_exception_fp_ieee_invalid_op 0
		.amdhsa_exception_fp_denorm_src 0
		.amdhsa_exception_fp_ieee_div_zero 0
		.amdhsa_exception_fp_ieee_overflow 0
		.amdhsa_exception_fp_ieee_underflow 0
		.amdhsa_exception_fp_ieee_inexact 0
		.amdhsa_exception_int_div_zero 0
	.end_amdhsa_kernel

; #define LAS __attribute__((address_space(3)))
; __global__ void __launch_bounds__(512) fwd_kernel(Args args) {
;     extern __shared__ __attribute__((aligned(16))) unsigned char lds_raw[];
;     Frame F; F.lds = (LAS unsigned char*)lds_raw; F.tid = threadIdx.x; F.lane = F.tid & 63; F.wave = __builtin_amdgcn_readfirstlane(F.tid >> 6); F.G = gridDim.x; F.bid = blockIdx.x;
amdhsa.kernels:
  - .agpr_count:     0
    .args:
      - .offset:         0
        .size:           248
        .value_kind:     by_value
      - .offset:         248
        .size:           4
        .value_kind:     hidden_block_count_x
      - .offset:         252
        .size:           4
        .value_kind:     hidden_block_count_y
      - .offset:         256
        .size:           4
        .value_kind:     hidden_block_count_z
      - .offset:         260
        .size:           2
        .value_kind:     hidden_group_size_x
      - .offset:         262
        .size:           2
        .value_kind:     hidden_group_size_y
      - .offset:         264
        .size:           2
        .value_kind:     hidden_group_size_z
      - .offset:         266
        .size:           2
        .value_kind:     hidden_remainder_x
      - .offset:         268
        .size:           2
        .value_kind:     hidden_remainder_y
      - .offset:         270
        .size:           2
        .value_kind:     hidden_remainder_z
      - .offset:         288
        .size:           8
        .value_kind:     hidden_global_offset_x
      - .offset:         296
        .size:           8
        .value_kind:     hidden_global_offset_y
      - .offset:         304
        .size:           8
        .value_kind:     hidden_global_offset_z
      - .offset:         312
        .size:           2
        .value_kind:     hidden_grid_dims
      - .offset:         336
        .size:           8
        .value_kind:     hidden_multigrid_sync_arg
      - .offset:         368
        .size:           4
        .value_kind:     hidden_dynamic_lds_size
    .group_segment_fixed_size: 0
    .kernarg_segment_align: 8
    .kernarg_segment_size: 504
    .language:       OpenCL C
    .language_version:
      - 2
      - 0
    .max_flat_workgroup_size: 512
    .name:           _Z10fwd_kernel4Args
    .private_segment_fixed_size: 0
    .sgpr_count:     106
    .sgpr_spill_count: 22
    .symbol:         _Z10fwd_kernel4Args.kd
    .uniform_work_group_size: 1
    .uses_dynamic_stack: false
    .vgpr_count:     250
    .vgpr_spill_count: 0
    .wavefront_size: 64
